# phase-5 work queue split per XCD so each XCD keeps the K/V of two batch-head pairs in its L2
# speedup vs baseline: 1.0129x; 1.0068x over previous
; DI int TIDX() { int t = __builtin_amdgcn_workitem_id_x(); asm volatile("" : "+v"(t)); return t; }
; DI void phase5(const Params& p, int l, unsigned char* smem) {
;   __shared__ int s_task;
;   int* ctr = (int*)(p.ws + W_CTR) + l;
;   while (true) {
;     __syncthreads();
;     if (TIDX() == 0) s_task = atomicAdd(ctr, 1);
;     __syncthreads();
.LBB0_770:
	v_writelane_b32 v254, s42, 56
	s_nop 1
	v_writelane_b32 v254, s43, 57
	s_or_b64 exec, exec, s[2:3]
	v_readlane_b32 s2, v254, 49
	s_barrier
	s_ashr_i32 s3, s2, 31
	s_lshl_b64 s[4:5], s[2:3], 2
	s_add_u32 s3, s76, s4
	s_addc_u32 s4, s77, s5
	s_add_u32 s34, s3, 0x2ac8000
	s_addc_u32 s35, s4, 0
	s_getreg_b32 s5, hwreg(HW_REG_XCC_ID, 0, 4)
	s_and_b32 s5, s5, 7
	v_writelane_b32 v255, s5, 56
	s_lshl_b32 s5, s5, 4
	s_add_u32 s5, s5, 64
	s_add_u32 s34, s34, s5
	s_addc_u32 s35, s35, 0
	s_lshl_b32 s3, s2, 6
	v_writelane_b32 v254, s3, 58
	s_lshl_b32 s2, s2, 4
	v_writelane_b32 v254, s2, 59
	s_nop 0
	v_readlane_b32 s2, v254, 37
	v_readlane_b32 s3, v254, 38
	s_add_u32 s4, s2, 0x1898d000
	v_writelane_b32 v254, s4, 60
	s_addc_u32 s4, s3, 0
	s_add_u32 s80, s76, 0x7b6b700
	s_addc_u32 s81, s77, 0
	v_writelane_b32 v254, s4, 61
	s_add_u32 s2, s2, 0x4080000
	v_writelane_b32 v254, s2, 63
	s_addc_u32 s2, s3, 0
	v_writelane_b32 v255, s2, 0
	s_add_u32 s2, s76, 0x23ebcf00
	v_writelane_b32 v255, s2, 1
	s_addc_u32 s2, s77, 0
	v_writelane_b32 v255, s2, 2
	v_writelane_b32 v255, s80, 3
	s_nop 1
	v_writelane_b32 v255, s81, 4
	v_writelane_b32 v255, s40, 5
	s_nop 1
	v_writelane_b32 v255, s41, 6
	v_writelane_b32 v255, s34, 7
	s_nop 1
	v_writelane_b32 v255, s35, 8
	s_branch .LBB0_774

; DI int TIDX() { int t = __builtin_amdgcn_workitem_id_x(); asm volatile("" : "+v"(t)); return t; }
; DI void rwkv_scan_task(const Params& p, int srow0, int T, int h, int rq, const float* S0, float* Sout, int comb_bh, int comb_seg, unsigned char* smem) {
;   if (rq & 1) return;
;   float* ops = (float*)smem;
;   float* sc = ops + 2 * 16 * 384;
;   float* ybuf = sc + 64;
;   const int tid = TIDX(), i = tid >> 3, c8 = tid & 7, c0 = c8 * 8;
;   const int Rr = rq * 16 + i;
;   const float* RWW = (const float*)(p.ws + W_RWW); const u16* RWX = (const u16*)(p.ws + W_RWX); float* YRAW = (float*)(p.ws + W_YRAW);
;   f32x4v S[2];
;   if (S0) { S[0] = *(const f32x4v*)(S0 + Rr * 64 + c0); S[1] = *(const f32x4v*)(S0 + Rr * 64 + c0 + 4); }
;   else { S[0] = (f32x4v){0.f, 0.f, 0.f, 0.f}; S[1] = S[0]; }
; DI void phase5(const Params& p, int l, unsigned char* smem) {
;     ...
;   while (true) {
;     __syncthreads();
;     if (TIDX() == 0) s_task = atomicAdd(ctr, 1);
;     __syncthreads();
;     int q = s_task;
;     if (q >= PH5_TASKS) break;
;     int task = q < 1024 ? ((q & 1) ? 512 + (q >> 1) : (q >> 1)) : q;
;     phase5_task(p, l, task, smem);
.LBB0_778:
	s_or_b64 exec, exec, s[2:3]
	s_waitcnt lgkmcnt(0)
	s_barrier
	ds_read_b32 v0, v184
	s_movk_i32 s2, 0x16f
	s_waitcnt lgkmcnt(0)
	v_cmp_lt_i32_e32 vcc, s2, v0
	v_readfirstlane_b32 s4, v0
	s_mov_b64 s[2:3], -1
	s_cbranch_vccnz .LBB0_773
	v_readlane_b32 s2, v255, 56
	s_nop 3
	s_cmpk_lt_u32 s4, 0x80
	s_cbranch_scc0 .Lp5q_hi
	s_lshr_b32 s3, s4, 1
	s_bitcmp1_b32 s4, 0
	s_cbranch_scc1 .Lp5q_odd
	s_and_b32 s50, s3, 1
	s_lshl_b32 s2, s2, 1
	s_add_i32 s50, s50, s2
	s_lshl_b32 s50, s50, 5
	s_lshr_b32 s3, s3, 1
	s_add_i32 s50, s50, s3
	s_branch .Lp5_task
.Lp5q_odd:
	s_cmpk_lt_u32 s3, 16
	s_cbranch_scc0 .Lp5q_prompt_lo
	s_lshr_b32 s50, s3, 3
	s_lshl_b32 s50, s50, 6
	s_and_b32 s3, s3, 7
	s_add_i32 s50, s50, s3
	s_lshl_b32 s2, s2, 3
	s_add_i32 s50, s50, s2
	s_addk_i32 s50, 0x200
	s_branch .Lp5_task
.Lp5q_prompt_lo:
	s_sub_i32 s3, s3, 16
	s_branch .Lp5q_prompt
.Lp5q_hi:
	s_sub_i32 s3, s4, 0x80
	s_cmpk_lt_u32 s3, 0xd0
	s_cbranch_scc0 .Lp5q_sscan
	s_add_i32 s3, s3, 48
.Lp5q_prompt:
	s_lshr_b32 s50, s3, 2
	s_lshl_b32 s50, s50, 5
	s_lshl_b32 s4, s3, 3
	s_and_b32 s4, s4, 16
	s_add_i32 s50, s50, s4
	s_and_b32 s3, s3, 1
	s_add_i32 s50, s50, s3
	s_lshl_b32 s2, s2, 1
	s_add_i32 s50, s50, s2
	s_addk_i32 s50, 0x280
	s_branch .Lp5_task
.Lp5q_sscan:
	s_sub_i32 s3, s3, 0xd0
	s_lshl_b32 s2, s2, 5
	s_add_i32 s50, s3, s2
	s_addk_i32 s50, 0xa80
.Lp5_task:
	s_cmpk_gt_i32 s50, 0x1ff
	s_mov_b64 s[2:3], -1
	s_cbranch_scc0 .LBB0_833
	s_cmpk_gt_u32 s50, 0xa7f
	s_cbranch_scc0 .LBB0_794
	s_bitcmp1_b32 s50, 0
	s_cselect_b64 s[2:3], -1, 0
	s_and_b64 vcc, exec, s[2:3]
	s_cbranch_vccnz .LBB0_793
	s_add_i32 s2, s50, 0xfffff580
	v_readlane_b32 s4, v254, 33
	s_lshr_b32 s6, s2, 5
	v_readlane_b32 s5, v254, 34
	s_lshl_b32 s2, s6, 3
	v_readlane_b32 s3, v254, 58
	s_load_dwordx2 s[4:5], s[4:5], 0x10
	s_bfe_u32 s20, s50, 0x30002
	s_add_i32 s2, s2, s3
	v_mov_b32_e32 v70, v160
	s_lshl_b32 s7, s50, 4
	s_or_b32 s2, s2, s20
	s_and_b32 s21, s7, 32
	v_ashrrev_i32_e32 v68, 3, v70
	s_ashr_i32 s3, s2, 31
	v_and_b32_e32 v69, 7, v70
	v_add_u32_e32 v1, s21, v68
	s_lshl_b64 s[2:3], s[2:3], 12
	v_lshlrev_b32_e32 v0, 3, v69
	s_waitcnt vmcnt(2)
	v_lshlrev_b32_e32 v54, 6, v1
	s_waitcnt lgkmcnt(0)
	s_cmp_eq_u64 s[4:5], 0
	s_waitcnt vmcnt(1)
	v_lshlrev_b32_e32 v52, 2, v0
	v_ashrrev_i32_e32 v55, 31, v54
	s_cbranch_scc1 .LBB0_785
	s_lshl_b64 s[8:9], s[2:3], 2
	s_add_u32 s4, s4, s8
	s_addc_u32 s5, s5, s9
	v_lshl_add_u64 v[0:1], v[54:55], 2, s[4:5]
	v_mov_b32_e32 v53, v163
	v_lshl_add_u64 v[0:1], v[0:1], 0, v[52:53]
	global_load_dwordx4 v[40:43], v[0:1], off
	global_load_dwordx4 v[36:39], v[0:1], off offset:16
	s_branch .LBB0_786
